# code placement: 64-byte alignment of the eight GEMM K-loop head labels
# baseline (speedup 1.0000x reference)
; template <class Epi, bool ALIGN_EPI, bool ASLOT = false>
; __device__ __forceinline__ void gemm_phase(LAS unsigned char* lds, const Gemm g, const Sched& S, const Epi& E) {
;     ...
;         const bool has_next = S.next(ui + 1, nxt);
;         const char* nA = has_next ? (const char*)g.A + (size_t)nxt.z * g.zA + (size_t)nxt.pm * pstepA : cA; const char* nB = has_next ? (const char*)g.Bt + (size_t)nxt.z * g.zB + (size_t)nxt.pn * tstep : cB;
;     ...
;         for (int a = 0; a < 2; ++a)
; #pragma unroll
;             for (int b = 0; b < 2; ++b)
; #pragma unroll
;                 for (int m = 0; m < 4; ++m)
; #pragma unroll
;                     for (int n = 0; n < 2; ++n) acc[a][b][m][n] = (f32x4){0.f, 0.f, 0.f, 0.f};
.LBB0_121:
	s_ashr_i32 s7, s6, 31
	s_lshl_b64 s[10:11], s[6:7], 19
	s_add_u32 s10, s20, s10
	s_addc_u32 s11, s21, s11
	s_and_b64 s[12:13], s[36:37], exec
	s_cselect_b32 s7, s11, s15
	s_cselect_b32 s24, s10, s14
	s_ashr_i32 s9, s8, 31
	s_lshl_b64 s[12:13], s[8:9], 19
	s_add_u32 s12, s27, s12
	s_addc_u32 s13, s38, s13
	s_and_b64 s[20:21], s[36:37], exec
	s_cselect_b32 s9, s13, s19
	s_cselect_b32 s25, s12, s18
	s_add_u32 s14, s14, 0x40080
	s_addc_u32 s15, s15, 0
	s_add_u32 s46, s18, 0x100
	v_mov_b32_e32 v2, 0
	s_addc_u32 s47, s19, 0
	s_mov_b32 s48, -2
	v_mov_b32_e32 v3, v2
	v_mov_b32_e32 v4, v2
	v_mov_b32_e32 v5, v2
	v_mov_b32_e32 v6, v2
	v_mov_b32_e32 v7, v2
	v_mov_b32_e32 v8, v2
	v_mov_b32_e32 v9, v2
	v_mov_b32_e32 v18, v2
	v_mov_b32_e32 v19, v2
	v_mov_b32_e32 v20, v2
	v_mov_b32_e32 v21, v2
	v_mov_b32_e32 v22, v2
	v_mov_b32_e32 v23, v2
	v_mov_b32_e32 v24, v2
	v_mov_b32_e32 v25, v2
	v_mov_b32_e32 v34, v2
	v_mov_b32_e32 v35, v2
	v_mov_b32_e32 v36, v2
	v_mov_b32_e32 v37, v2
	v_mov_b32_e32 v38, v2
	v_mov_b32_e32 v39, v2
	v_mov_b32_e32 v40, v2
	v_mov_b32_e32 v41, v2
	v_mov_b32_e32 v50, v2
	v_mov_b32_e32 v51, v2
	v_mov_b32_e32 v52, v2
	v_mov_b32_e32 v53, v2
	v_mov_b32_e32 v54, v2
	v_mov_b32_e32 v55, v2
	v_mov_b32_e32 v56, v2
	v_mov_b32_e32 v57, v2
	v_mov_b32_e32 v10, v2
	v_mov_b32_e32 v11, v2
	v_mov_b32_e32 v12, v2
	v_mov_b32_e32 v13, v2
	v_mov_b32_e32 v14, v2
	v_mov_b32_e32 v15, v2
	v_mov_b32_e32 v16, v2
	v_mov_b32_e32 v17, v2
	v_mov_b32_e32 v26, v2
	v_mov_b32_e32 v27, v2
	v_mov_b32_e32 v28, v2
	v_mov_b32_e32 v29, v2
	v_mov_b32_e32 v30, v2
	v_mov_b32_e32 v31, v2
	v_mov_b32_e32 v32, v2
	v_mov_b32_e32 v33, v2
	v_mov_b32_e32 v42, v2
	v_mov_b32_e32 v43, v2
	v_mov_b32_e32 v44, v2
	v_mov_b32_e32 v45, v2
	v_mov_b32_e32 v46, v2
	v_mov_b32_e32 v47, v2
	v_mov_b32_e32 v48, v2
	v_mov_b32_e32 v49, v2
	v_mov_b32_e32 v58, v2
	v_mov_b32_e32 v59, v2
	v_mov_b32_e32 v60, v2
	v_mov_b32_e32 v61, v2
	v_mov_b32_e32 v62, v2
	v_mov_b32_e32 v63, v2
	v_mov_b32_e32 v64, v2
	v_mov_b32_e32 v65, v2
	v_mov_b32_e32 v66, v2
	v_mov_b32_e32 v67, v2
	v_mov_b32_e32 v68, v2
	v_mov_b32_e32 v69, v2
	v_mov_b32_e32 v70, v2
	v_mov_b32_e32 v71, v2
	v_mov_b32_e32 v72, v2
	v_mov_b32_e32 v73, v2
	v_mov_b32_e32 v82, v2
	v_mov_b32_e32 v83, v2
	v_mov_b32_e32 v84, v2
	v_mov_b32_e32 v85, v2
	v_mov_b32_e32 v86, v2
	v_mov_b32_e32 v87, v2
	v_mov_b32_e32 v88, v2
	v_mov_b32_e32 v89, v2
	v_mov_b32_e32 v98, v2
	v_mov_b32_e32 v99, v2
	v_mov_b32_e32 v100, v2
	v_mov_b32_e32 v101, v2
	v_mov_b32_e32 v102, v2
	v_mov_b32_e32 v103, v2
	v_mov_b32_e32 v104, v2
	v_mov_b32_e32 v105, v2
	v_mov_b32_e32 v114, v2
	v_mov_b32_e32 v115, v2
	v_mov_b32_e32 v116, v2
	v_mov_b32_e32 v117, v2
	v_mov_b32_e32 v118, v2
	v_mov_b32_e32 v119, v2
	v_mov_b32_e32 v120, v2
	v_mov_b32_e32 v121, v2
	v_mov_b32_e32 v74, v2
	v_mov_b32_e32 v75, v2
	v_mov_b32_e32 v76, v2
	v_mov_b32_e32 v77, v2
	v_mov_b32_e32 v78, v2
	v_mov_b32_e32 v79, v2
	v_mov_b32_e32 v80, v2
	v_mov_b32_e32 v81, v2
	v_mov_b32_e32 v90, v2
	v_mov_b32_e32 v91, v2
	v_mov_b32_e32 v92, v2
	v_mov_b32_e32 v93, v2
	v_mov_b32_e32 v94, v2
	v_mov_b32_e32 v95, v2
	v_mov_b32_e32 v96, v2
	v_mov_b32_e32 v97, v2
	v_mov_b32_e32 v106, v2
	v_mov_b32_e32 v107, v2
	v_mov_b32_e32 v108, v2
	v_mov_b32_e32 v109, v2
	v_mov_b32_e32 v110, v2
	v_mov_b32_e32 v111, v2
	v_mov_b32_e32 v112, v2
	v_mov_b32_e32 v113, v2
	v_mov_b32_e32 v122, v2
	v_mov_b32_e32 v123, v2
	v_mov_b32_e32 v124, v2
	v_mov_b32_e32 v125, v2
	v_mov_b32_e32 v126, v2
	v_mov_b32_e32 v127, v2
	v_mov_b32_e32 v128, v2
	v_mov_b32_e32 v129, v2
	.p2align	6

; template <class Epi, bool ALIGN_EPI, bool ASLOT = false>
; __device__ __forceinline__ void gemm_phase(LAS unsigned char* lds, const Gemm g, const Sched& S, const Epi& E) {
;     ...
;         const bool has_next = S.next(ui + 1, nxt);
;         const char* nA = has_next ? (const char*)g.A + (size_t)nxt.z * g.zA + (size_t)nxt.pm * pstepA : cA; const char* nB = has_next ? (const char*)g.Bt + (size_t)nxt.z * g.zB + (size_t)nxt.pn * tstep : cB;
;     ...
;         for (int a = 0; a < 2; ++a)
; #pragma unroll
;             for (int b = 0; b < 2; ++b)
; #pragma unroll
;                 for (int m = 0; m < 4; ++m)
; #pragma unroll
;                     for (int n = 0; n < 2; ++n) acc[a][b][m][n] = (f32x4){0.f, 0.f, 0.f, 0.f};
.LBB0_139:
	s_ashr_i32 s15, s14, 31
	s_lshl_b64 s[22:23], s[14:15], 19
	s_add_u32 s40, s31, s22
	s_addc_u32 s41, s34, s23
	s_and_b64 s[22:23], s[44:45], exec
	s_cselect_b32 s11, s41, s21
	s_cselect_b32 s13, s40, s20
	s_add_u32 s44, s20, 0x40080
	s_addc_u32 s45, s21, 0
	s_add_u32 s15, s18, 0x100
	v_mov_b32_e32 v2, 0
	s_addc_u32 s49, s19, 0
	s_mov_b32 s50, -2
	v_mov_b32_e32 v3, v2
	v_mov_b32_e32 v4, v2
	v_mov_b32_e32 v5, v2
	v_mov_b32_e32 v6, v2
	v_mov_b32_e32 v7, v2
	v_mov_b32_e32 v8, v2
	v_mov_b32_e32 v9, v2
	v_mov_b32_e32 v10, v2
	v_mov_b32_e32 v11, v2
	v_mov_b32_e32 v12, v2
	v_mov_b32_e32 v13, v2
	v_mov_b32_e32 v14, v2
	v_mov_b32_e32 v15, v2
	v_mov_b32_e32 v16, v2
	v_mov_b32_e32 v17, v2
	v_mov_b32_e32 v26, v2
	v_mov_b32_e32 v27, v2
	v_mov_b32_e32 v28, v2
	v_mov_b32_e32 v29, v2
	v_mov_b32_e32 v30, v2
	v_mov_b32_e32 v31, v2
	v_mov_b32_e32 v32, v2
	v_mov_b32_e32 v33, v2
	v_mov_b32_e32 v42, v2
	v_mov_b32_e32 v43, v2
	v_mov_b32_e32 v44, v2
	v_mov_b32_e32 v45, v2
	v_mov_b32_e32 v46, v2
	v_mov_b32_e32 v47, v2
	v_mov_b32_e32 v48, v2
	v_mov_b32_e32 v49, v2
	v_mov_b32_e32 v18, v2
	v_mov_b32_e32 v19, v2
	v_mov_b32_e32 v20, v2
	v_mov_b32_e32 v21, v2
	v_mov_b32_e32 v22, v2
	v_mov_b32_e32 v23, v2
	v_mov_b32_e32 v24, v2
	v_mov_b32_e32 v25, v2
	v_mov_b32_e32 v34, v2
	v_mov_b32_e32 v35, v2
	v_mov_b32_e32 v36, v2
	v_mov_b32_e32 v37, v2
	v_mov_b32_e32 v38, v2
	v_mov_b32_e32 v39, v2
	v_mov_b32_e32 v40, v2
	v_mov_b32_e32 v41, v2
	v_mov_b32_e32 v50, v2
	v_mov_b32_e32 v51, v2
	v_mov_b32_e32 v52, v2
	v_mov_b32_e32 v53, v2
	v_mov_b32_e32 v54, v2
	v_mov_b32_e32 v55, v2
	v_mov_b32_e32 v56, v2
	v_mov_b32_e32 v57, v2
	v_mov_b32_e32 v58, v2
	v_mov_b32_e32 v59, v2
	v_mov_b32_e32 v60, v2
	v_mov_b32_e32 v61, v2
	v_mov_b32_e32 v62, v2
	v_mov_b32_e32 v63, v2
	v_mov_b32_e32 v64, v2
	v_mov_b32_e32 v65, v2
	v_mov_b32_e32 v66, v2
	v_mov_b32_e32 v67, v2
	v_mov_b32_e32 v68, v2
	v_mov_b32_e32 v69, v2
	v_mov_b32_e32 v70, v2
	v_mov_b32_e32 v71, v2
	v_mov_b32_e32 v72, v2
	v_mov_b32_e32 v73, v2
	v_mov_b32_e32 v74, v2
	v_mov_b32_e32 v75, v2
	v_mov_b32_e32 v76, v2
	v_mov_b32_e32 v77, v2
	v_mov_b32_e32 v78, v2
	v_mov_b32_e32 v79, v2
	v_mov_b32_e32 v80, v2
	v_mov_b32_e32 v81, v2
	v_mov_b32_e32 v90, v2
	v_mov_b32_e32 v91, v2
	v_mov_b32_e32 v92, v2
	v_mov_b32_e32 v93, v2
	v_mov_b32_e32 v94, v2
	v_mov_b32_e32 v95, v2
	v_mov_b32_e32 v96, v2
	v_mov_b32_e32 v97, v2
	v_mov_b32_e32 v106, v2
	v_mov_b32_e32 v107, v2
	v_mov_b32_e32 v108, v2
	v_mov_b32_e32 v109, v2
	v_mov_b32_e32 v110, v2
	v_mov_b32_e32 v111, v2
	v_mov_b32_e32 v112, v2
	v_mov_b32_e32 v113, v2
	v_mov_b32_e32 v82, v2
	v_mov_b32_e32 v83, v2
	v_mov_b32_e32 v84, v2
	v_mov_b32_e32 v85, v2
	v_mov_b32_e32 v86, v2
	v_mov_b32_e32 v87, v2
	v_mov_b32_e32 v88, v2
	v_mov_b32_e32 v89, v2
	v_mov_b32_e32 v98, v2
	v_mov_b32_e32 v99, v2
	v_mov_b32_e32 v100, v2
	v_mov_b32_e32 v101, v2
	v_mov_b32_e32 v102, v2
	v_mov_b32_e32 v103, v2
	v_mov_b32_e32 v104, v2
	v_mov_b32_e32 v105, v2
	v_mov_b32_e32 v114, v2
	v_mov_b32_e32 v115, v2
	v_mov_b32_e32 v116, v2
	v_mov_b32_e32 v117, v2
	v_mov_b32_e32 v118, v2
	v_mov_b32_e32 v119, v2
	v_mov_b32_e32 v120, v2
	v_mov_b32_e32 v121, v2
	v_mov_b32_e32 v122, v2
	v_mov_b32_e32 v123, v2
	v_mov_b32_e32 v124, v2
	v_mov_b32_e32 v125, v2
	v_mov_b32_e32 v126, v2
	v_mov_b32_e32 v127, v2
	v_mov_b32_e32 v128, v2
	v_mov_b32_e32 v129, v2
	.p2align	6

; #define PG8_STAGE(bufoff, gbase, voff) do { _Pragma("unroll") for (int _i = 0; _i < 2; ++_i) \
;         __builtin_amdgcn_global_load_lds((const unsigned*)((const char*)(gbase) + (voff)[_i]), (LAS unsigned*)(lds + (bufoff) + ldsw + _i * 8192), 16, 0, 0); } while (0)
; #define PG8_WAIT_V(n) asm volatile("s_waitcnt vmcnt(" #n ")" ::: "memory")
; #define PG8_BAR __builtin_amdgcn_s_barrier()
; template <class Epi, bool ALIGN_EPI, bool ASLOT = false>
; __device__ __forceinline__ void gemm_phase(LAS unsigned char* lds, const Gemm g, const Sched& S, const Epi& E) {
;     ...
;     const int tid = tid_, wid = __builtin_amdgcn_readfirstlane(tid >> 6), lane = tid & 63, wr = wid >> 2, wc = wid & 3, fr = lane & 15, fq = lane >> 4;
;     const int K = g.K, nt = K / BK;
;     unsigned voffA[2], voffB[2];
; #pragma unroll
;     for (int i = 0; i < 2; ++i) { int R, C; stage_rc(tid * 16 + i * 8192, R, C); const int Rb = (R & ~31) + perm32(R & 31);
;         voffA[i] = (unsigned)(R * K + C) * 2u; voffB[i] = (unsigned)(Rb * K + C) * 2u; }
;     const size_t kstep = (size_t)(BK * 2);
;     const size_t hstep = (size_t)HALF * K * 2;
;     const size_t tstep = 2 * hstep;
;     const unsigned ldsw = (unsigned)wid * 1024u;
;     const int aoff = lds_byte(wr * 64 + fr, fq * 8), boff = lds_byte(wc * 32 + fr, fq * 8);
;     ...
;     Unit cur, nxt; int ui = 0;
;     if (!S.next(0, cur)) return;
;     f32x4 acc[2][2][4][2];
; #pragma unroll
;     for (int a = 0; a < 2; ++a)
; #pragma unroll
;         for (int b = 0; b < 2; ++b)
; #pragma unroll
;             for (int m = 0; m < 4; ++m)
; #pragma unroll
;                 for (int n = 0; n < 2; ++n) acc[a][b][m][n] = (f32x4){0.f, 0.f, 0.f, 0.f};
;     bf16x8 At[4][2], B0[2][2], B1[2][2];
;     const size_t pstepA = ASLOT ? SLOTB : tstep;
;     const char* cA = (const char*)g.A + (size_t)cur.z * g.zA + (size_t)cur.pm * pstepA; const char* cB = (const char*)g.Bt + (size_t)cur.z * g.zB + (size_t)cur.pn * tstep;
;     PG8_STAGE(PG8_SB(0, 0), cB, voffB); PG8_STAGE(PG8_SB(0, 1), cB + hstep, voffB); PG8_STAGE(PG8_SA(0, 0), cA, voffA); PG8_STAGE(PG8_SA(0, 1), cA + hstep, voffA);
;     if (wr == 1) PG8_BAR;
;     PG8_WAIT_V(2); PG8_BAR;
;     PG8_STAGE(PG8_SB(1, 0), cB + kstep, voffB); PG8_STAGE(PG8_SA(1, 0), cA + kstep, voffA); PG8_STAGE(PG8_SB(1, 1), cB + hstep + kstep, voffB);
;     PG8_WAIT_V(6); PG8_BAR;
.LBB0_174:
	v_lshrrev_b32_e32 v20, 1, v11
	v_and_b32_e32 v141, 24, v20
	v_and_b32_e32 v15, 15, v11
	v_lshlrev_b32_e32 v20, 1, v141
	v_lshlrev_b32_e32 v11, 2, v11
	v_lshl_or_b32 v140, s10, 6, v15
	v_lshl_or_b32 v15, v15, 6, v20
	s_lshl_b32 s10, s10, 13
	v_and_b32_e32 v11, 32, v11
	v_bitop3_b32 v20, v15, s10, v11 bitop3:0xde
	s_lshl_b32 s10, s11, 5
	v_mov_b32_e32 v131, v1
	s_and_b32 s24, s10, 0x60
	s_add_i32 m0, s18, 0x18000
	v_lshl_add_u64 v[2:3], v[2:3], 0, s[16:17]
	v_lshl_add_u64 v[16:17], s[38:39], 0, v[130:131]
	v_mov_b32_e32 v133, v1
	s_lshl_b32 s10, s24, 7
	s_waitcnt vmcnt(2)
	s_barrier
	global_load_lds_dwordx4 v[2:3], off
	v_lshl_add_u64 v[2:3], v[4:5], 0, s[16:17]
	s_add_i32 m0, s18, 0x1a000
	s_add_i32 s25, s18, 0x8000
	s_add_i32 s27, s18, 0xa000
	v_lshl_add_u64 v[18:19], s[38:39], 0, v[132:133]
	v_bitop3_b32 v142, v15, s10, v11 bitop3:0xde
	global_load_lds_dwordx4 v[2:3], off
	v_lshl_add_u64 v[2:3], v[16:17], 0, s[16:17]
	s_mov_b32 m0, s25
	s_add_u32 s10, s8, 0xb0080
	global_load_lds_dwordx4 v[2:3], off
	v_lshl_add_u64 v[2:3], v[18:19], 0, s[16:17]
	s_mov_b32 m0, s27
	s_addc_u32 s11, s9, 0
	global_load_lds_dwordx4 v[2:3], off
	s_add_i32 m0, s18, 0x1c000
	v_lshl_add_u64 v[2:3], s[10:11], 0, v[0:1]
	global_load_lds_dwordx4 v[2:3], off
	v_lshl_add_u64 v[2:3], s[10:11], 0, v[134:135]
	s_add_i32 m0, s18, 0x1e000
	s_movk_i32 s14, 0xb00
	global_load_lds_dwordx4 v[2:3], off
	v_lshrrev_b32_e32 v3, 1, v6
	v_mul_lo_u32 v2, v7, s14
	v_mad_u64_u32 v[2:3], s[10:11], v3, s31, v[2:3]
	v_or_b32_e32 v2, v2, v8
	v_readlane_b32 s12, v254, 19
	v_add_lshl_u32 v2, v2, v9, 1
	v_mov_b32_e32 v3, v1
	v_readlane_b32 s13, v254, 20
	s_waitcnt vmcnt(6)
	s_mov_b32 s37, -2
	v_add_u32_e32 v143, 0, v20
	v_lshl_add_u64 v[136:137], s[12:13], 0, v[2:3]
	v_lshrrev_b32_e32 v3, 1, v10
	v_mul_lo_u32 v2, v13, s14
	v_mad_u64_u32 v[2:3], s[10:11], v3, s31, v[2:3]
	v_or_b32_e32 v2, v2, v12
	v_add_lshl_u32 v2, v2, v14, 1
	v_mov_b32_e32 v3, v1
	v_readlane_b32 s10, v254, 23
	v_readlane_b32 s11, v254, 63
	v_lshl_add_u64 v[138:139], s[12:13], 0, v[2:3]
	s_add_u32 s34, s10, s11
	v_readlane_b32 s10, v254, 24
	v_mov_b32_e32 v2, 0
	s_addc_u32 s36, s10, 0
	s_mov_b64 s[10:11], 0
	v_mov_b32_e32 v3, v2
	v_mov_b32_e32 v4, v2
	v_mov_b32_e32 v5, v2
	v_mov_b32_e32 v6, v2
	v_mov_b32_e32 v7, v2
	v_mov_b32_e32 v8, v2
	v_mov_b32_e32 v9, v2
	v_mov_b32_e32 v10, v2
	v_mov_b32_e32 v11, v2
	v_mov_b32_e32 v12, v2
	v_mov_b32_e32 v13, v2
	v_mov_b32_e32 v14, v2
	v_mov_b32_e32 v15, v2
	v_mov_b32_e32 v16, v2
	v_mov_b32_e32 v17, v2
	v_mov_b32_e32 v26, v2
	v_mov_b32_e32 v27, v2
	v_mov_b32_e32 v28, v2
	v_mov_b32_e32 v29, v2
	v_mov_b32_e32 v30, v2
	v_mov_b32_e32 v31, v2
	v_mov_b32_e32 v32, v2
	v_mov_b32_e32 v33, v2
	v_mov_b32_e32 v42, v2
	v_mov_b32_e32 v43, v2
	v_mov_b32_e32 v44, v2
	v_mov_b32_e32 v45, v2
	v_mov_b32_e32 v46, v2
	v_mov_b32_e32 v47, v2
	v_mov_b32_e32 v48, v2
	v_mov_b32_e32 v49, v2
	v_mov_b32_e32 v18, v2
	v_mov_b32_e32 v19, v2
	v_mov_b32_e32 v20, v2
	v_mov_b32_e32 v21, v2
	v_mov_b32_e32 v22, v2
	v_mov_b32_e32 v23, v2
	v_mov_b32_e32 v24, v2
	v_mov_b32_e32 v25, v2
	v_mov_b32_e32 v34, v2
	v_mov_b32_e32 v35, v2
	v_mov_b32_e32 v36, v2
	v_mov_b32_e32 v37, v2
	v_mov_b32_e32 v38, v2
	v_mov_b32_e32 v39, v2
	v_mov_b32_e32 v40, v2
	v_mov_b32_e32 v41, v2
	v_mov_b32_e32 v50, v2
	v_mov_b32_e32 v51, v2
	v_mov_b32_e32 v52, v2
	v_mov_b32_e32 v53, v2
	v_mov_b32_e32 v54, v2
	v_mov_b32_e32 v55, v2
	v_mov_b32_e32 v56, v2
	v_mov_b32_e32 v57, v2
	v_mov_b32_e32 v58, v2
	v_mov_b32_e32 v59, v2
	v_mov_b32_e32 v60, v2
	v_mov_b32_e32 v61, v2
	v_mov_b32_e32 v62, v2
	v_mov_b32_e32 v63, v2
	v_mov_b32_e32 v64, v2
	v_mov_b32_e32 v65, v2
	v_mov_b32_e32 v66, v2
	v_mov_b32_e32 v67, v2
	v_mov_b32_e32 v68, v2
	v_mov_b32_e32 v69, v2
	v_mov_b32_e32 v70, v2
	v_mov_b32_e32 v71, v2
	v_mov_b32_e32 v72, v2
	v_mov_b32_e32 v73, v2
	v_mov_b32_e32 v74, v2
	v_mov_b32_e32 v75, v2
	v_mov_b32_e32 v76, v2
	v_mov_b32_e32 v77, v2
	v_mov_b32_e32 v78, v2
	v_mov_b32_e32 v79, v2
	v_mov_b32_e32 v80, v2
	v_mov_b32_e32 v81, v2
	v_mov_b32_e32 v90, v2
	v_mov_b32_e32 v91, v2
	v_mov_b32_e32 v92, v2
	v_mov_b32_e32 v93, v2
	v_mov_b32_e32 v94, v2
	v_mov_b32_e32 v95, v2
	v_mov_b32_e32 v96, v2
	v_mov_b32_e32 v97, v2
	v_mov_b32_e32 v106, v2
	v_mov_b32_e32 v107, v2
	v_mov_b32_e32 v108, v2
	v_mov_b32_e32 v109, v2
	v_mov_b32_e32 v110, v2
	v_mov_b32_e32 v111, v2
	v_mov_b32_e32 v112, v2
	v_mov_b32_e32 v113, v2
	v_mov_b32_e32 v82, v2
	v_mov_b32_e32 v83, v2
	v_mov_b32_e32 v84, v2
	v_mov_b32_e32 v85, v2
	v_mov_b32_e32 v86, v2
	v_mov_b32_e32 v87, v2
	v_mov_b32_e32 v88, v2
	v_mov_b32_e32 v89, v2
	v_mov_b32_e32 v98, v2
	v_mov_b32_e32 v99, v2
	v_mov_b32_e32 v100, v2
	v_mov_b32_e32 v101, v2
	v_mov_b32_e32 v102, v2
	v_mov_b32_e32 v103, v2
	v_mov_b32_e32 v104, v2
	v_mov_b32_e32 v105, v2
	v_mov_b32_e32 v114, v2
	v_mov_b32_e32 v115, v2
	v_mov_b32_e32 v116, v2
	v_mov_b32_e32 v117, v2
	v_mov_b32_e32 v118, v2
	v_mov_b32_e32 v119, v2
	v_mov_b32_e32 v120, v2
	v_mov_b32_e32 v121, v2
	v_mov_b32_e32 v122, v2
	v_mov_b32_e32 v123, v2
	v_mov_b32_e32 v124, v2
	v_mov_b32_e32 v125, v2
	v_mov_b32_e32 v126, v2
	v_mov_b32_e32 v127, v2
	v_mov_b32_e32 v128, v2
	v_mov_b32_e32 v129, v2
	v_readlane_b32 s31, v254, 58
	v_readlane_b32 s35, v254, 59
	s_barrier
	.p2align	6

; template <class Epi, bool ALIGN_EPI, bool ASLOT = false>
; __device__ __forceinline__ void gemm_phase(LAS unsigned char* lds, const Gemm g, const Sched& S, const Epi& E) {
;     ...
;         const bool has_next = S.next(ui + 1, nxt);
;         const char* nA = has_next ? (const char*)g.A + (size_t)nxt.z * g.zA + (size_t)nxt.pm * pstepA : cA; const char* nB = has_next ? (const char*)g.Bt + (size_t)nxt.z * g.zB + (size_t)nxt.pn * tstep : cB;
;     ...
;         for (int a = 0; a < 2; ++a)
; #pragma unroll
;             for (int b = 0; b < 2; ++b)
; #pragma unroll
;                 for (int m = 0; m < 4; ++m)
; #pragma unroll
;                     for (int n = 0; n < 2; ++n) acc[a][b][m][n] = (f32x4){0.f, 0.f, 0.f, 0.f};
.LBB0_299:
	s_ashr_i32 s43, s42, 31
	s_lshl_b64 s[18:19], s[42:43], 19
	v_readlane_b32 s22, v254, 52
	v_readlane_b32 s23, v254, 53
	s_add_u32 s46, s22, s18
	s_addc_u32 s47, s23, s19
	s_and_b64 s[18:19], s[38:39], exec
	s_cselect_b32 s3, s47, s1
	s_cselect_b32 s24, s46, s0
	s_ashr_i32 s45, s44, 31
	s_lshl_b64 s[18:19], s[44:45], 19
	s_add_u32 s48, s20, s18
	s_addc_u32 s49, s21, s19
	s_and_b64 s[18:19], s[38:39], exec
	s_cselect_b32 s25, s49, s15
	s_cselect_b32 s41, s48, s14
	s_add_u32 s0, s0, 0x40080
	s_addc_u32 s1, s1, 0
	s_add_u32 s43, s14, 0x100
	s_waitcnt lgkmcnt(0)
	v_mov_b32_e32 v2, 0
	s_addc_u32 s45, s15, 0
	s_mov_b32 s57, -2
	v_mov_b32_e32 v3, v2
	v_mov_b32_e32 v4, v2
	v_mov_b32_e32 v5, v2
	v_mov_b32_e32 v6, v2
	v_mov_b32_e32 v7, v2
	v_mov_b32_e32 v8, v2
	v_mov_b32_e32 v9, v2
	v_mov_b32_e32 v18, v2
	v_mov_b32_e32 v19, v2
	v_mov_b32_e32 v20, v2
	v_mov_b32_e32 v21, v2
	v_mov_b32_e32 v22, v2
	v_mov_b32_e32 v23, v2
	v_mov_b32_e32 v24, v2
	v_mov_b32_e32 v25, v2
	v_mov_b32_e32 v34, v2
	v_mov_b32_e32 v35, v2
	v_mov_b32_e32 v36, v2
	v_mov_b32_e32 v37, v2
	v_mov_b32_e32 v38, v2
	v_mov_b32_e32 v39, v2
	v_mov_b32_e32 v40, v2
	v_mov_b32_e32 v41, v2
	v_mov_b32_e32 v50, v2
	v_mov_b32_e32 v51, v2
	v_mov_b32_e32 v52, v2
	v_mov_b32_e32 v53, v2
	v_mov_b32_e32 v54, v2
	v_mov_b32_e32 v55, v2
	v_mov_b32_e32 v56, v2
	v_mov_b32_e32 v57, v2
	v_mov_b32_e32 v10, v2
	v_mov_b32_e32 v11, v2
	v_mov_b32_e32 v12, v2
	v_mov_b32_e32 v13, v2
	v_mov_b32_e32 v14, v2
	v_mov_b32_e32 v15, v2
	v_mov_b32_e32 v16, v2
	v_mov_b32_e32 v17, v2
	v_mov_b32_e32 v26, v2
	v_mov_b32_e32 v27, v2
	v_mov_b32_e32 v28, v2
	v_mov_b32_e32 v29, v2
	v_mov_b32_e32 v30, v2
	v_mov_b32_e32 v31, v2
	v_mov_b32_e32 v32, v2
	v_mov_b32_e32 v33, v2
	v_mov_b32_e32 v42, v2
	v_mov_b32_e32 v43, v2
	v_mov_b32_e32 v44, v2
	v_mov_b32_e32 v45, v2
	v_mov_b32_e32 v46, v2
	v_mov_b32_e32 v47, v2
	v_mov_b32_e32 v48, v2
	v_mov_b32_e32 v49, v2
	v_mov_b32_e32 v58, v2
	v_mov_b32_e32 v59, v2
	v_mov_b32_e32 v60, v2
	v_mov_b32_e32 v61, v2
	v_mov_b32_e32 v62, v2
	v_mov_b32_e32 v63, v2
	v_mov_b32_e32 v64, v2
	v_mov_b32_e32 v65, v2
	v_mov_b32_e32 v66, v2
	v_mov_b32_e32 v67, v2
	v_mov_b32_e32 v68, v2
	v_mov_b32_e32 v69, v2
	v_mov_b32_e32 v70, v2
	v_mov_b32_e32 v71, v2
	v_mov_b32_e32 v72, v2
	v_mov_b32_e32 v73, v2
	v_mov_b32_e32 v82, v2
	v_mov_b32_e32 v83, v2
	v_mov_b32_e32 v84, v2
	v_mov_b32_e32 v85, v2
	v_mov_b32_e32 v86, v2
	v_mov_b32_e32 v87, v2
	v_mov_b32_e32 v88, v2
	v_mov_b32_e32 v89, v2
	v_mov_b32_e32 v98, v2
	v_mov_b32_e32 v99, v2
	v_mov_b32_e32 v100, v2
	v_mov_b32_e32 v101, v2
	v_mov_b32_e32 v102, v2
	v_mov_b32_e32 v103, v2
	v_mov_b32_e32 v104, v2
	v_mov_b32_e32 v105, v2
	v_mov_b32_e32 v114, v2
	v_mov_b32_e32 v115, v2
	v_mov_b32_e32 v116, v2
	v_mov_b32_e32 v117, v2
	v_mov_b32_e32 v118, v2
	v_mov_b32_e32 v119, v2
	v_mov_b32_e32 v120, v2
	v_mov_b32_e32 v121, v2
	v_mov_b32_e32 v74, v2
	v_mov_b32_e32 v75, v2
	v_mov_b32_e32 v76, v2
	v_mov_b32_e32 v77, v2
	v_mov_b32_e32 v78, v2
	v_mov_b32_e32 v79, v2
	v_mov_b32_e32 v80, v2
	v_mov_b32_e32 v81, v2
	v_mov_b32_e32 v90, v2
	v_mov_b32_e32 v91, v2
	v_mov_b32_e32 v92, v2
	v_mov_b32_e32 v93, v2
	v_mov_b32_e32 v94, v2
	v_mov_b32_e32 v95, v2
	v_mov_b32_e32 v96, v2
	v_mov_b32_e32 v97, v2
	v_mov_b32_e32 v106, v2
	v_mov_b32_e32 v107, v2
	v_mov_b32_e32 v108, v2
	v_mov_b32_e32 v109, v2
	v_mov_b32_e32 v110, v2
	v_mov_b32_e32 v111, v2
	v_mov_b32_e32 v112, v2
	v_mov_b32_e32 v113, v2
	v_mov_b32_e32 v122, v2
	v_mov_b32_e32 v123, v2
	v_mov_b32_e32 v124, v2
	v_mov_b32_e32 v125, v2
	v_mov_b32_e32 v126, v2
	v_mov_b32_e32 v127, v2
	v_mov_b32_e32 v128, v2
	v_mov_b32_e32 v129, v2
	.p2align	6

; template <class Epi, bool ALIGN_EPI, bool ASLOT = false>
; __device__ __forceinline__ void gemm_phase(LAS unsigned char* lds, const Gemm g, const Sched& S, const Epi& E) {
;     ...
;     for (;;) {
;         const bool has_next = S.next(ui + 1, nxt);
;         const char* nA = has_next ? (const char*)g.A + (size_t)nxt.z * g.zA + (size_t)nxt.pm * pstepA : cA; const char* nB = has_next ? (const char*)g.Bt + (size_t)nxt.z * g.zB + (size_t)nxt.pn * tstep : cB;
;         for (int t = 0; t < nt; t += 2) {
.Lbr_keep_acc:
	.p2align	6

; #define PG8_STAGE(bufoff, gbase, voff) do { _Pragma("unroll") for (int _i = 0; _i < 2; ++_i) \
;         __builtin_amdgcn_global_load_lds((const unsigned*)((const char*)(gbase) + (voff)[_i]), (LAS unsigned*)(lds + (bufoff) + ldsw + _i * 8192), 16, 0, 0); } while (0)
; #define PG8_WAIT_V(n) asm volatile("s_waitcnt vmcnt(" #n ")" ::: "memory")
; #define PG8_BAR __builtin_amdgcn_s_barrier()
; template <class Epi, bool ALIGN_EPI, bool ASLOT = false>
; __device__ __forceinline__ void gemm_phase(LAS unsigned char* lds, const Gemm g, const Sched& S, const Epi& E) {
;     ...
;     const int tid = tid_, wid = __builtin_amdgcn_readfirstlane(tid >> 6), lane = tid & 63, wr = wid >> 2, wc = wid & 3, fr = lane & 15, fq = lane >> 4;
;     const int K = g.K, nt = K / BK;
;     unsigned voffA[2], voffB[2];
; #pragma unroll
;     for (int i = 0; i < 2; ++i) { int R, C; stage_rc(tid * 16 + i * 8192, R, C); const int Rb = (R & ~31) + perm32(R & 31);
;         voffA[i] = (unsigned)(R * K + C) * 2u; voffB[i] = (unsigned)(Rb * K + C) * 2u; }
;     const size_t kstep = (size_t)(BK * 2);
;     const size_t hstep = (size_t)HALF * K * 2;
;     const size_t tstep = 2 * hstep;
;     const unsigned ldsw = (unsigned)wid * 1024u;
;     const int aoff = lds_byte(wr * 64 + fr, fq * 8), boff = lds_byte(wc * 32 + fr, fq * 8);
;     ...
;     Unit cur, nxt; int ui = 0;
;     if (!S.next(0, cur)) return;
;     f32x4 acc[2][2][4][2];
; #pragma unroll
;     for (int a = 0; a < 2; ++a)
; #pragma unroll
;         for (int b = 0; b < 2; ++b)
; #pragma unroll
;             for (int m = 0; m < 4; ++m)
; #pragma unroll
;                 for (int n = 0; n < 2; ++n) acc[a][b][m][n] = (f32x4){0.f, 0.f, 0.f, 0.f};
;     bf16x8 At[4][2], B0[2][2], B1[2][2];
;     const size_t pstepA = ASLOT ? SLOTB : tstep;
;     const char* cA = (const char*)g.A + (size_t)cur.z * g.zA + (size_t)cur.pm * pstepA; const char* cB = (const char*)g.Bt + (size_t)cur.z * g.zB + (size_t)cur.pn * tstep;
;     PG8_STAGE(PG8_SB(0, 0), cB, voffB); PG8_STAGE(PG8_SB(0, 1), cB + hstep, voffB); PG8_STAGE(PG8_SA(0, 0), cA, voffA); PG8_STAGE(PG8_SA(0, 1), cA + hstep, voffA);
;     if (wr == 1) PG8_BAR;
;     PG8_WAIT_V(2); PG8_BAR;
;     PG8_STAGE(PG8_SB(1, 0), cB + kstep, voffB); PG8_STAGE(PG8_SA(1, 0), cA + kstep, voffA); PG8_STAGE(PG8_SB(1, 1), cB + hstep + kstep, voffB);
;     PG8_WAIT_V(6); PG8_BAR;
.LBB0_782:
	v_lshrrev_b32_e32 v18, 1, v10
	v_and_b32_e32 v141, 24, v18
	v_and_b32_e32 v13, 15, v10
	v_lshlrev_b32_e32 v18, 1, v141
	v_lshlrev_b32_e32 v10, 2, v10
	v_lshl_or_b32 v140, s4, 6, v13
	v_lshl_or_b32 v13, v13, 6, v18
	s_lshl_b32 s4, s4, 13
	v_and_b32_e32 v10, 32, v10
	v_bitop3_b32 v18, v13, s4, v10 bitop3:0xde
	s_lshl_b32 s4, s5, 5
	v_mov_b32_e32 v131, v1
	s_and_b32 s14, s4, 0x60
	s_add_i32 m0, s10, 0x18000
	v_lshl_add_u64 v[2:3], v[2:3], 0, s[16:17]
	v_lshl_add_u64 v[14:15], s[36:37], 0, v[130:131]
	v_mov_b32_e32 v133, v1
	s_lshl_b32 s4, s14, 7
	s_waitcnt vmcnt(2)
	s_barrier
	global_load_lds_dwordx4 v[2:3], off
	v_lshl_add_u64 v[2:3], v[4:5], 0, s[16:17]
	s_add_i32 m0, s10, 0x1a000
	s_add_i32 s15, s10, 0x8000
	s_add_i32 s18, s10, 0xa000
	v_lshl_add_u64 v[16:17], s[36:37], 0, v[132:133]
	v_bitop3_b32 v142, v13, s4, v10 bitop3:0xde
	global_load_lds_dwordx4 v[2:3], off
	v_lshl_add_u64 v[2:3], v[14:15], 0, s[16:17]
	s_mov_b32 m0, s15
	s_add_u32 s4, s0, 0x40080
	global_load_lds_dwordx4 v[2:3], off
	v_lshl_add_u64 v[2:3], v[16:17], 0, s[16:17]
	s_mov_b32 m0, s18
	s_addc_u32 s5, s1, 0
	global_load_lds_dwordx4 v[2:3], off
	s_add_i32 m0, s10, 0x1c000
	v_lshl_add_u64 v[2:3], s[4:5], 0, v[0:1]
	global_load_lds_dwordx4 v[2:3], off
	v_lshl_add_u64 v[2:3], s[4:5], 0, v[134:135]
	s_add_i32 m0, s10, 0x1e000
	v_readlane_b32 s4, v254, 31
	global_load_lds_dwordx4 v[2:3], off
	v_lshlrev_b32_e32 v2, 14, v6
	v_and_b32_e32 v2, 0xffff8000, v2
	v_lshl_add_u32 v2, v7, 11, v2
	v_and_b32_e32 v3, 1, v6
	v_lshl_or_b32 v2, v3, 6, v2
	v_lshl_add_u32 v2, v8, 1, v2
	v_mov_b32_e32 v3, v1
	v_readlane_b32 s5, v254, 32
	s_waitcnt vmcnt(6)
	s_mov_b32 s21, -2
	v_add_u32_e32 v143, 0, v18
	v_lshl_add_u64 v[136:137], s[4:5], 0, v[2:3]
	v_lshlrev_b32_e32 v2, 14, v9
	v_and_b32_e32 v2, 0xffff8000, v2
	v_lshl_add_u32 v2, v11, 11, v2
	v_and_b32_e32 v3, 1, v9
	v_lshl_or_b32 v2, v3, 6, v2
	v_lshl_add_u32 v2, v12, 1, v2
	v_mov_b32_e32 v3, v1
	v_lshl_add_u64 v[138:139], s[4:5], 0, v[2:3]
	v_readlane_b32 s4, v254, 34
	v_readlane_b32 s5, v254, 63
	s_add_u32 s19, s4, s5
	v_readlane_b32 s4, v254, 35
	v_mov_b32_e32 v2, 0
	s_addc_u32 s20, s4, 0
	s_mov_b64 s[4:5], 0
	v_mov_b32_e32 v3, v2
	v_mov_b32_e32 v4, v2
	v_mov_b32_e32 v5, v2
	v_mov_b32_e32 v6, v2
	v_mov_b32_e32 v7, v2
	v_mov_b32_e32 v8, v2
	v_mov_b32_e32 v9, v2
	v_mov_b32_e32 v10, v2
	v_mov_b32_e32 v11, v2
	v_mov_b32_e32 v12, v2
	v_mov_b32_e32 v13, v2
	v_mov_b32_e32 v14, v2
	v_mov_b32_e32 v15, v2
	v_mov_b32_e32 v16, v2
	v_mov_b32_e32 v17, v2
	v_mov_b32_e32 v26, v2
	v_mov_b32_e32 v27, v2
	v_mov_b32_e32 v28, v2
	v_mov_b32_e32 v29, v2
	v_mov_b32_e32 v30, v2
	v_mov_b32_e32 v31, v2
	v_mov_b32_e32 v32, v2
	v_mov_b32_e32 v33, v2
	v_mov_b32_e32 v42, v2
	v_mov_b32_e32 v43, v2
	v_mov_b32_e32 v44, v2
	v_mov_b32_e32 v45, v2
	v_mov_b32_e32 v46, v2
	v_mov_b32_e32 v47, v2
	v_mov_b32_e32 v48, v2
	v_mov_b32_e32 v49, v2
	v_mov_b32_e32 v18, v2
	v_mov_b32_e32 v19, v2
	v_mov_b32_e32 v20, v2
	v_mov_b32_e32 v21, v2
	v_mov_b32_e32 v22, v2
	v_mov_b32_e32 v23, v2
	v_mov_b32_e32 v24, v2
	v_mov_b32_e32 v25, v2
	v_mov_b32_e32 v34, v2
	v_mov_b32_e32 v35, v2
	v_mov_b32_e32 v36, v2
	v_mov_b32_e32 v37, v2
	v_mov_b32_e32 v38, v2
	v_mov_b32_e32 v39, v2
	v_mov_b32_e32 v40, v2
	v_mov_b32_e32 v41, v2
	v_mov_b32_e32 v50, v2
	v_mov_b32_e32 v51, v2
	v_mov_b32_e32 v52, v2
	v_mov_b32_e32 v53, v2
	v_mov_b32_e32 v54, v2
	v_mov_b32_e32 v55, v2
	v_mov_b32_e32 v56, v2
	v_mov_b32_e32 v57, v2
	v_mov_b32_e32 v58, v2
	v_mov_b32_e32 v59, v2
	v_mov_b32_e32 v60, v2
	v_mov_b32_e32 v61, v2
	v_mov_b32_e32 v62, v2
	v_mov_b32_e32 v63, v2
	v_mov_b32_e32 v64, v2
	v_mov_b32_e32 v65, v2
	v_mov_b32_e32 v66, v2
	v_mov_b32_e32 v67, v2
	v_mov_b32_e32 v68, v2
	v_mov_b32_e32 v69, v2
	v_mov_b32_e32 v70, v2
	v_mov_b32_e32 v71, v2
	v_mov_b32_e32 v72, v2
	v_mov_b32_e32 v73, v2
	v_mov_b32_e32 v74, v2
	v_mov_b32_e32 v75, v2
	v_mov_b32_e32 v76, v2
	v_mov_b32_e32 v77, v2
	v_mov_b32_e32 v78, v2
	v_mov_b32_e32 v79, v2
	v_mov_b32_e32 v80, v2
	v_mov_b32_e32 v81, v2
	v_mov_b32_e32 v90, v2
	v_mov_b32_e32 v91, v2
	v_mov_b32_e32 v92, v2
	v_mov_b32_e32 v93, v2
	v_mov_b32_e32 v94, v2
	v_mov_b32_e32 v95, v2
	v_mov_b32_e32 v96, v2
	v_mov_b32_e32 v97, v2
	v_mov_b32_e32 v106, v2
	v_mov_b32_e32 v107, v2
	v_mov_b32_e32 v108, v2
	v_mov_b32_e32 v109, v2
	v_mov_b32_e32 v110, v2
	v_mov_b32_e32 v111, v2
	v_mov_b32_e32 v112, v2
	v_mov_b32_e32 v113, v2
	v_mov_b32_e32 v82, v2
	v_mov_b32_e32 v83, v2
	v_mov_b32_e32 v84, v2
	v_mov_b32_e32 v85, v2
	v_mov_b32_e32 v86, v2
	v_mov_b32_e32 v87, v2
	v_mov_b32_e32 v88, v2
	v_mov_b32_e32 v89, v2
	v_mov_b32_e32 v98, v2
	v_mov_b32_e32 v99, v2
	v_mov_b32_e32 v100, v2
	v_mov_b32_e32 v101, v2
	v_mov_b32_e32 v102, v2
	v_mov_b32_e32 v103, v2
	v_mov_b32_e32 v104, v2
	v_mov_b32_e32 v105, v2
	v_mov_b32_e32 v114, v2
	v_mov_b32_e32 v115, v2
	v_mov_b32_e32 v116, v2
	v_mov_b32_e32 v117, v2
	v_mov_b32_e32 v118, v2
	v_mov_b32_e32 v119, v2
	v_mov_b32_e32 v120, v2
	v_mov_b32_e32 v121, v2
	v_mov_b32_e32 v122, v2
	v_mov_b32_e32 v123, v2
	v_mov_b32_e32 v124, v2
	v_mov_b32_e32 v125, v2
	v_mov_b32_e32 v126, v2
	v_mov_b32_e32 v127, v2
	v_mov_b32_e32 v128, v2
	v_mov_b32_e32 v129, v2
	s_barrier
	.p2align	6

; template <class Epi, bool ALIGN_EPI, bool ASLOT = false>
; __device__ __forceinline__ void gemm_phase(LAS unsigned char* lds, const Gemm g, const Sched& S, const Epi& E) {
;     ...
;         const bool has_next = S.next(ui + 1, nxt);
;         const char* nA = has_next ? (const char*)g.A + (size_t)nxt.z * g.zA + (size_t)nxt.pm * pstepA : cA; const char* nB = has_next ? (const char*)g.Bt + (size_t)nxt.z * g.zB + (size_t)nxt.pn * tstep : cB;
;     ...
;         for (int a = 0; a < 2; ++a)
; #pragma unroll
;             for (int b = 0; b < 2; ++b)
; #pragma unroll
;                 for (int m = 0; m < 4; ++m)
; #pragma unroll
;                     for (int n = 0; n < 2; ++n) acc[a][b][m][n] = (f32x4){0.f, 0.f, 0.f, 0.f};
.LBB0_852:
	s_ashr_i32 s9, s8, 31
	s_lshl_b64 s[12:13], s[8:9], 19
	s_add_u32 s12, s22, s12
	s_addc_u32 s13, s23, s13
	s_and_b64 s[14:15], s[40:41], exec
	s_cselect_b32 s9, s13, s21
	s_cselect_b32 s24, s12, s20
	s_ashr_i32 s11, s10, 31
	s_lshl_b64 s[14:15], s[10:11], 19
	s_add_u32 s14, s27, s14
	s_addc_u32 s15, s38, s15
	s_and_b64 s[22:23], s[40:41], exec
	s_cselect_b32 s11, s15, s19
	s_cselect_b32 s25, s14, s18
	s_add_u32 s36, s20, 0x40080
	s_addc_u32 s37, s21, 0
	s_add_u32 s48, s18, 0x100
	v_mov_b32_e32 v2, 0
	s_addc_u32 s49, s19, 0
	s_mov_b32 s50, -2
	v_mov_b32_e32 v3, v2
	v_mov_b32_e32 v4, v2
	v_mov_b32_e32 v5, v2
	v_mov_b32_e32 v6, v2
	v_mov_b32_e32 v7, v2
	v_mov_b32_e32 v8, v2
	v_mov_b32_e32 v9, v2
	v_mov_b32_e32 v18, v2
	v_mov_b32_e32 v19, v2
	v_mov_b32_e32 v20, v2
	v_mov_b32_e32 v21, v2
	v_mov_b32_e32 v22, v2
	v_mov_b32_e32 v23, v2
	v_mov_b32_e32 v24, v2
	v_mov_b32_e32 v25, v2
	v_mov_b32_e32 v34, v2
	v_mov_b32_e32 v35, v2
	v_mov_b32_e32 v36, v2
	v_mov_b32_e32 v37, v2
	v_mov_b32_e32 v38, v2
	v_mov_b32_e32 v39, v2
	v_mov_b32_e32 v40, v2
	v_mov_b32_e32 v41, v2
	v_mov_b32_e32 v50, v2
	v_mov_b32_e32 v51, v2
	v_mov_b32_e32 v52, v2
	v_mov_b32_e32 v53, v2
	v_mov_b32_e32 v54, v2
	v_mov_b32_e32 v55, v2
	v_mov_b32_e32 v56, v2
	v_mov_b32_e32 v57, v2
	v_mov_b32_e32 v10, v2
	v_mov_b32_e32 v11, v2
	v_mov_b32_e32 v12, v2
	v_mov_b32_e32 v13, v2
	v_mov_b32_e32 v14, v2
	v_mov_b32_e32 v15, v2
	v_mov_b32_e32 v16, v2
	v_mov_b32_e32 v17, v2
	v_mov_b32_e32 v26, v2
	v_mov_b32_e32 v27, v2
	v_mov_b32_e32 v28, v2
	v_mov_b32_e32 v29, v2
	v_mov_b32_e32 v30, v2
	v_mov_b32_e32 v31, v2
	v_mov_b32_e32 v32, v2
	v_mov_b32_e32 v33, v2
	v_mov_b32_e32 v42, v2
	v_mov_b32_e32 v43, v2
	v_mov_b32_e32 v44, v2
	v_mov_b32_e32 v45, v2
	v_mov_b32_e32 v46, v2
	v_mov_b32_e32 v47, v2
	v_mov_b32_e32 v48, v2
	v_mov_b32_e32 v49, v2
	v_mov_b32_e32 v58, v2
	v_mov_b32_e32 v59, v2
	v_mov_b32_e32 v60, v2
	v_mov_b32_e32 v61, v2
	v_mov_b32_e32 v62, v2
	v_mov_b32_e32 v63, v2
	v_mov_b32_e32 v64, v2
	v_mov_b32_e32 v65, v2
	v_mov_b32_e32 v66, v2
	v_mov_b32_e32 v67, v2
	v_mov_b32_e32 v68, v2
	v_mov_b32_e32 v69, v2
	v_mov_b32_e32 v70, v2
	v_mov_b32_e32 v71, v2
	v_mov_b32_e32 v72, v2
	v_mov_b32_e32 v73, v2
	v_mov_b32_e32 v82, v2
	v_mov_b32_e32 v83, v2
	v_mov_b32_e32 v84, v2
	v_mov_b32_e32 v85, v2
	v_mov_b32_e32 v86, v2
	v_mov_b32_e32 v87, v2
	v_mov_b32_e32 v88, v2
	v_mov_b32_e32 v89, v2
	v_mov_b32_e32 v98, v2
	v_mov_b32_e32 v99, v2
	v_mov_b32_e32 v100, v2
	v_mov_b32_e32 v101, v2
	v_mov_b32_e32 v102, v2
	v_mov_b32_e32 v103, v2
	v_mov_b32_e32 v104, v2
	v_mov_b32_e32 v105, v2
	v_mov_b32_e32 v114, v2
	v_mov_b32_e32 v115, v2
	v_mov_b32_e32 v116, v2
	v_mov_b32_e32 v117, v2
	v_mov_b32_e32 v118, v2
	v_mov_b32_e32 v119, v2
	v_mov_b32_e32 v120, v2
	v_mov_b32_e32 v121, v2
	v_mov_b32_e32 v74, v2
	v_mov_b32_e32 v75, v2
	v_mov_b32_e32 v76, v2
	v_mov_b32_e32 v77, v2
	v_mov_b32_e32 v78, v2
	v_mov_b32_e32 v79, v2
	v_mov_b32_e32 v80, v2
	v_mov_b32_e32 v81, v2
	v_mov_b32_e32 v90, v2
	v_mov_b32_e32 v91, v2
	v_mov_b32_e32 v92, v2
	v_mov_b32_e32 v93, v2
	v_mov_b32_e32 v94, v2
	v_mov_b32_e32 v95, v2
	v_mov_b32_e32 v96, v2
	v_mov_b32_e32 v97, v2
	v_mov_b32_e32 v106, v2
	v_mov_b32_e32 v107, v2
	v_mov_b32_e32 v108, v2
	v_mov_b32_e32 v109, v2
	v_mov_b32_e32 v110, v2
	v_mov_b32_e32 v111, v2
	v_mov_b32_e32 v112, v2
	v_mov_b32_e32 v113, v2
	v_mov_b32_e32 v122, v2
	v_mov_b32_e32 v123, v2
	v_mov_b32_e32 v124, v2
	v_mov_b32_e32 v125, v2
	v_mov_b32_e32 v126, v2
	v_mov_b32_e32 v127, v2
	v_mov_b32_e32 v128, v2
	v_mov_b32_e32 v129, v2
	.p2align	6

; #define PG8_STAGE(bufoff, gbase, voff) do { _Pragma("unroll") for (int _i = 0; _i < 2; ++_i) \
;         __builtin_amdgcn_global_load_lds((const unsigned*)((const char*)(gbase) + (voff)[_i]), (LAS unsigned*)(lds + (bufoff) + ldsw + _i * 8192), 16, 0, 0); } while (0)
; #define PG8_WAIT_V(n) asm volatile("s_waitcnt vmcnt(" #n ")" ::: "memory")
; #define PG8_BAR __builtin_amdgcn_s_barrier()
; template <class Epi, bool ALIGN_EPI, bool ASLOT = false>
; __device__ __forceinline__ void gemm_phase(LAS unsigned char* lds, const Gemm g, const Sched& S, const Epi& E) {
;     ...
;     const int tid = tid_, wid = __builtin_amdgcn_readfirstlane(tid >> 6), lane = tid & 63, wr = wid >> 2, wc = wid & 3, fr = lane & 15, fq = lane >> 4;
;     const int K = g.K, nt = K / BK;
;     unsigned voffA[2], voffB[2];
; #pragma unroll
;     for (int i = 0; i < 2; ++i) { int R, C; stage_rc(tid * 16 + i * 8192, R, C); const int Rb = (R & ~31) + perm32(R & 31);
;         voffA[i] = (unsigned)(R * K + C) * 2u; voffB[i] = (unsigned)(Rb * K + C) * 2u; }
;     const size_t kstep = (size_t)(BK * 2);
;     const size_t hstep = (size_t)HALF * K * 2;
;     const size_t tstep = 2 * hstep;
;     const unsigned ldsw = (unsigned)wid * 1024u;
;     const int aoff = lds_byte(wr * 64 + fr, fq * 8), boff = lds_byte(wc * 32 + fr, fq * 8);
;     ...
;     Unit cur, nxt; int ui = 0;
;     if (!S.next(0, cur)) return;
;     f32x4 acc[2][2][4][2];
; #pragma unroll
;     for (int a = 0; a < 2; ++a)
; #pragma unroll
;         for (int b = 0; b < 2; ++b)
; #pragma unroll
;             for (int m = 0; m < 4; ++m)
; #pragma unroll
;                 for (int n = 0; n < 2; ++n) acc[a][b][m][n] = (f32x4){0.f, 0.f, 0.f, 0.f};
;     bf16x8 At[4][2], B0[2][2], B1[2][2];
;     const size_t pstepA = ASLOT ? SLOTB : tstep;
;     const char* cA = (const char*)g.A + (size_t)cur.z * g.zA + (size_t)cur.pm * pstepA; const char* cB = (const char*)g.Bt + (size_t)cur.z * g.zB + (size_t)cur.pn * tstep;
;     PG8_STAGE(PG8_SB(0, 0), cB, voffB); PG8_STAGE(PG8_SB(0, 1), cB + hstep, voffB); PG8_STAGE(PG8_SA(0, 0), cA, voffA); PG8_STAGE(PG8_SA(0, 1), cA + hstep, voffA);
;     if (wr == 1) PG8_BAR;
;     PG8_WAIT_V(2); PG8_BAR;
;     PG8_STAGE(PG8_SB(1, 0), cB + kstep, voffB); PG8_STAGE(PG8_SA(1, 0), cA + kstep, voffA); PG8_STAGE(PG8_SB(1, 1), cB + hstep + kstep, voffB);
;     PG8_WAIT_V(6); PG8_BAR;
.LBB0_883:
	v_lshrrev_b32_e32 v20, 1, v11
	v_and_b32_e32 v141, 24, v20
	v_and_b32_e32 v15, 15, v11
	v_lshlrev_b32_e32 v20, 1, v141
	v_lshlrev_b32_e32 v11, 2, v11
	v_lshl_or_b32 v140, s6, 6, v15
	v_lshl_or_b32 v15, v15, 6, v20
	s_lshl_b32 s6, s6, 13
	v_and_b32_e32 v11, 32, v11
	v_bitop3_b32 v20, v15, s6, v11 bitop3:0xde
	s_lshl_b32 s6, s7, 5
	v_mov_b32_e32 v131, v1
	s_and_b32 s18, s6, 0x60
	s_add_i32 m0, s12, 0x18000
	v_lshl_add_u64 v[2:3], v[2:3], 0, s[16:17]
	v_lshl_add_u64 v[16:17], s[36:37], 0, v[130:131]
	v_mov_b32_e32 v133, v1
	s_lshl_b32 s6, s18, 7
	s_waitcnt vmcnt(2)
	s_barrier
	global_load_lds_dwordx4 v[2:3], off
	v_lshl_add_u64 v[2:3], v[4:5], 0, s[16:17]
	s_add_i32 m0, s12, 0x1a000
	s_add_i32 s19, s12, 0x8000
	s_add_i32 s20, s12, 0xa000
	v_lshl_add_u64 v[18:19], s[36:37], 0, v[132:133]
	v_bitop3_b32 v142, v15, s6, v11 bitop3:0xde
	global_load_lds_dwordx4 v[2:3], off
	v_lshl_add_u64 v[2:3], v[16:17], 0, s[16:17]
	s_mov_b32 m0, s19
	s_add_u32 s6, s0, 0xb0080
	global_load_lds_dwordx4 v[2:3], off
	v_lshl_add_u64 v[2:3], v[18:19], 0, s[16:17]
	s_mov_b32 m0, s20
	s_addc_u32 s7, s1, 0
	global_load_lds_dwordx4 v[2:3], off
	s_add_i32 m0, s12, 0x1c000
	v_lshl_add_u64 v[2:3], s[6:7], 0, v[0:1]
	global_load_lds_dwordx4 v[2:3], off
	v_lshl_add_u64 v[2:3], s[6:7], 0, v[134:135]
	s_add_i32 m0, s12, 0x1e000
	s_movk_i32 s11, 0xb00
	global_load_lds_dwordx4 v[2:3], off
	v_lshrrev_b32_e32 v3, 1, v6
	v_mul_lo_u32 v2, v8, s11
	s_mov_b32 s10, 0xb000
	v_mad_u64_u32 v[2:3], s[6:7], v3, s10, v[2:3]
	v_or_b32_e32 v2, v2, v7
	v_readlane_b32 s8, v254, 19
	v_add_lshl_u32 v2, v2, v9, 1
	v_mov_b32_e32 v3, v1
	v_readlane_b32 s9, v254, 20
	s_waitcnt vmcnt(6)
	s_mov_b32 s25, -2
	v_add_u32_e32 v143, 0, v20
	v_lshl_add_u64 v[136:137], s[8:9], 0, v[2:3]
	v_lshrrev_b32_e32 v3, 1, v10
	v_mul_lo_u32 v2, v13, s11
	v_mad_u64_u32 v[2:3], s[6:7], v3, s10, v[2:3]
	v_or_b32_e32 v2, v2, v12
	v_add_lshl_u32 v2, v2, v14, 1
	v_mov_b32_e32 v3, v1
	v_readlane_b32 s6, v254, 38
	v_readlane_b32 s7, v254, 63
	v_lshl_add_u64 v[138:139], s[8:9], 0, v[2:3]
	s_add_u32 s21, s6, s7
	v_readlane_b32 s6, v254, 39
	v_mov_b32_e32 v2, 0
	s_addc_u32 s24, s6, 0
	s_mov_b64 s[6:7], 0
	v_mov_b32_e32 v3, v2
	v_mov_b32_e32 v4, v2
	v_mov_b32_e32 v5, v2
	v_mov_b32_e32 v6, v2
	v_mov_b32_e32 v7, v2
	v_mov_b32_e32 v8, v2
	v_mov_b32_e32 v9, v2
	v_mov_b32_e32 v10, v2
	v_mov_b32_e32 v11, v2
	v_mov_b32_e32 v12, v2
	v_mov_b32_e32 v13, v2
	v_mov_b32_e32 v14, v2
	v_mov_b32_e32 v15, v2
	v_mov_b32_e32 v16, v2
	v_mov_b32_e32 v17, v2
	v_mov_b32_e32 v26, v2
	v_mov_b32_e32 v27, v2
	v_mov_b32_e32 v28, v2
	v_mov_b32_e32 v29, v2
	v_mov_b32_e32 v30, v2
	v_mov_b32_e32 v31, v2
	v_mov_b32_e32 v32, v2
	v_mov_b32_e32 v33, v2
	v_mov_b32_e32 v42, v2
	v_mov_b32_e32 v43, v2
	v_mov_b32_e32 v44, v2
	v_mov_b32_e32 v45, v2
	v_mov_b32_e32 v46, v2
	v_mov_b32_e32 v47, v2
	v_mov_b32_e32 v48, v2
	v_mov_b32_e32 v49, v2
	v_mov_b32_e32 v18, v2
	v_mov_b32_e32 v19, v2
	v_mov_b32_e32 v20, v2
	v_mov_b32_e32 v21, v2
	v_mov_b32_e32 v22, v2
	v_mov_b32_e32 v23, v2
	v_mov_b32_e32 v24, v2
	v_mov_b32_e32 v25, v2
	v_mov_b32_e32 v34, v2
	v_mov_b32_e32 v35, v2
	v_mov_b32_e32 v36, v2
	v_mov_b32_e32 v37, v2
	v_mov_b32_e32 v38, v2
	v_mov_b32_e32 v39, v2
	v_mov_b32_e32 v40, v2
	v_mov_b32_e32 v41, v2
	v_mov_b32_e32 v50, v2
	v_mov_b32_e32 v51, v2
	v_mov_b32_e32 v52, v2
	v_mov_b32_e32 v53, v2
	v_mov_b32_e32 v54, v2
	v_mov_b32_e32 v55, v2
	v_mov_b32_e32 v56, v2
	v_mov_b32_e32 v57, v2
	v_mov_b32_e32 v58, v2
	v_mov_b32_e32 v59, v2
	v_mov_b32_e32 v60, v2
	v_mov_b32_e32 v61, v2
	v_mov_b32_e32 v62, v2
	v_mov_b32_e32 v63, v2
	v_mov_b32_e32 v64, v2
	v_mov_b32_e32 v65, v2
	v_mov_b32_e32 v66, v2
	v_mov_b32_e32 v67, v2
	v_mov_b32_e32 v68, v2
	v_mov_b32_e32 v69, v2
	v_mov_b32_e32 v70, v2
	v_mov_b32_e32 v71, v2
	v_mov_b32_e32 v72, v2
	v_mov_b32_e32 v73, v2
	v_mov_b32_e32 v74, v2
	v_mov_b32_e32 v75, v2
	v_mov_b32_e32 v76, v2
	v_mov_b32_e32 v77, v2
	v_mov_b32_e32 v78, v2
	v_mov_b32_e32 v79, v2
	v_mov_b32_e32 v80, v2
	v_mov_b32_e32 v81, v2
	v_mov_b32_e32 v90, v2
	v_mov_b32_e32 v91, v2
	v_mov_b32_e32 v92, v2
	v_mov_b32_e32 v93, v2
	v_mov_b32_e32 v94, v2
	v_mov_b32_e32 v95, v2
	v_mov_b32_e32 v96, v2
	v_mov_b32_e32 v97, v2
	v_mov_b32_e32 v106, v2
	v_mov_b32_e32 v107, v2
	v_mov_b32_e32 v108, v2
	v_mov_b32_e32 v109, v2
	v_mov_b32_e32 v110, v2
	v_mov_b32_e32 v111, v2
	v_mov_b32_e32 v112, v2
	v_mov_b32_e32 v113, v2
	v_mov_b32_e32 v82, v2
	v_mov_b32_e32 v83, v2
	v_mov_b32_e32 v84, v2
	v_mov_b32_e32 v85, v2
	v_mov_b32_e32 v86, v2
	v_mov_b32_e32 v87, v2
	v_mov_b32_e32 v88, v2
	v_mov_b32_e32 v89, v2
	v_mov_b32_e32 v98, v2
	v_mov_b32_e32 v99, v2
	v_mov_b32_e32 v100, v2
	v_mov_b32_e32 v101, v2
	v_mov_b32_e32 v102, v2
	v_mov_b32_e32 v103, v2
	v_mov_b32_e32 v104, v2
	v_mov_b32_e32 v105, v2
	v_mov_b32_e32 v114, v2
	v_mov_b32_e32 v115, v2
	v_mov_b32_e32 v116, v2
	v_mov_b32_e32 v117, v2
	v_mov_b32_e32 v118, v2
	v_mov_b32_e32 v119, v2
	v_mov_b32_e32 v120, v2
	v_mov_b32_e32 v121, v2
	v_mov_b32_e32 v122, v2
	v_mov_b32_e32 v123, v2
	v_mov_b32_e32 v124, v2
	v_mov_b32_e32 v125, v2
	v_mov_b32_e32 v126, v2
	v_mov_b32_e32 v127, v2
	v_mov_b32_e32 v128, v2
	v_mov_b32_e32 v129, v2
	v_readlane_b32 s30, v254, 58
	v_readlane_b32 s38, v254, 59
	s_barrier
	.p2align	6
